# nt also on the once-read Q block loads of FoX and MLA unit setup
# baseline (speedup 1.0000x reference)
.LBB0_337:
	s_or_b64 exec, exec, s[8:9]
	s_ashr_i32 s0, s6, 4
	s_ashr_i32 s1, s0, 31
	s_lshl_b32 s7, s6, 6
	s_lshl_b64 s[0:1], s[0:1], 23
	s_and_b32 s7, s7, 0x3c0
	s_or_b32 s0, s0, s7
	s_lshl_b64 s[36:37], s[0:1], 1
	s_add_u32 s30, s70, s36
	s_addc_u32 s31, s71, s37
	v_bfe_u32 v12, v133, 5, 1
	v_lshlrev_b64 v[10:11], 11, v[2:3]
	v_lshl_add_u64 v[10:11], s[30:31], 0, v[10:11]
	v_lshlrev_b32_e32 v100, 4, v12
	v_lshl_add_u64 v[10:11], v[10:11], 0, v[100:101]
	global_load_dwordx4 v[96:99], v[10:11], off nt
	global_load_dwordx4 v[92:95], v[10:11], off offset:32 nt
	global_load_dwordx4 v[88:91], v[10:11], off offset:64 nt
	global_load_dwordx4 v[84:87], v[10:11], off offset:96 nt
	v_cmp_lt_i32_e64 s[0:1], v123, v122
	v_and_b32_e32 v135, 63, v133
	s_waitcnt vmcnt(3)
	v_and_b32_e32 v13, 0xffff0000, v96
	v_cndmask_b32_e64 v3, v1, v123, s[0:1]
	s_lshl_b32 s0, s6, 1
	s_ashr_i32 s1, s0, 31
	s_lshl_b64 s[0:1], s[0:1], 2
	s_add_u32 s0, s45, s0
	s_addc_u32 s1, s52, s1
	global_load_dwordx2 v[10:11], v101, s[0:1]
	v_and_b32_e32 v15, 0xffff0000, v97
	v_lshlrev_b32_e32 v131, 2, v3
	v_lshlrev_b32_e32 v3, 16, v96
	v_lshlrev_b32_e32 v14, 16, v97
	v_and_b32_e32 v17, 0xffff0000, v98
	v_mul_f32_e32 v13, v13, v13
	v_mul_f32_e32 v15, v15, v15
	v_lshlrev_b32_e32 v16, 16, v98
	v_and_b32_e32 v19, 0xffff0000, v99
	v_mul_f32_e32 v17, v17, v17
	v_fmac_f32_e32 v13, v3, v3
	v_fmac_f32_e32 v15, v14, v14
	v_lshlrev_b32_e32 v18, 16, v99
	s_waitcnt vmcnt(3)
	v_and_b32_e32 v21, 0xffff0000, v92
	v_mul_f32_e32 v19, v19, v19
	v_fmac_f32_e32 v17, v16, v16
	v_add_f32_e32 v3, v13, v15
	v_lshlrev_b32_e32 v20, 16, v92
	v_and_b32_e32 v23, 0xffff0000, v93
	v_mul_f32_e32 v21, v21, v21
	v_fmac_f32_e32 v19, v18, v18
	v_add_f32_e32 v3, v17, v3
	v_lshlrev_b32_e32 v22, 16, v93
	v_and_b32_e32 v25, 0xffff0000, v94
	v_mul_f32_e32 v23, v23, v23
	v_fmac_f32_e32 v21, v20, v20
	v_add_f32_e32 v3, v19, v3
	v_lshlrev_b32_e32 v24, 16, v94
	v_and_b32_e32 v27, 0xffff0000, v95
	v_mul_f32_e32 v25, v25, v25
	v_fmac_f32_e32 v23, v22, v22
	v_add_f32_e32 v3, v21, v3
	v_lshlrev_b32_e32 v26, 16, v95
	s_waitcnt vmcnt(2)
	v_and_b32_e32 v29, 0xffff0000, v88
	v_mul_f32_e32 v27, v27, v27
	v_fmac_f32_e32 v25, v24, v24
	v_add_f32_e32 v3, v23, v3
	v_lshlrev_b32_e32 v28, 16, v88
	v_and_b32_e32 v31, 0xffff0000, v89
	v_mul_f32_e32 v29, v29, v29
	v_fmac_f32_e32 v27, v26, v26
	v_add_f32_e32 v3, v25, v3
	v_lshlrev_b32_e32 v30, 16, v89
	v_and_b32_e32 v33, 0xffff0000, v90
	v_mul_f32_e32 v31, v31, v31
	v_fmac_f32_e32 v29, v28, v28
	v_add_f32_e32 v3, v27, v3
	v_lshlrev_b32_e32 v32, 16, v90
	v_and_b32_e32 v35, 0xffff0000, v91
	v_mul_f32_e32 v33, v33, v33
	v_fmac_f32_e32 v31, v30, v30
	v_add_f32_e32 v3, v29, v3
	v_lshlrev_b32_e32 v34, 16, v91
	s_waitcnt vmcnt(1)
	v_and_b32_e32 v37, 0xffff0000, v84
	v_mul_f32_e32 v35, v35, v35
	v_fmac_f32_e32 v33, v32, v32
	v_add_f32_e32 v3, v31, v3
	v_lshlrev_b32_e32 v36, 16, v84
	v_and_b32_e32 v39, 0xffff0000, v85
	v_mul_f32_e32 v37, v37, v37
	v_fmac_f32_e32 v35, v34, v34
	v_add_f32_e32 v3, v33, v3
	v_lshlrev_b32_e32 v38, 16, v85
	v_and_b32_e32 v41, 0xffff0000, v86
	v_mul_f32_e32 v39, v39, v39
	v_fmac_f32_e32 v37, v36, v36
	v_add_f32_e32 v3, v35, v3
	v_lshlrev_b32_e32 v40, 16, v86
	v_and_b32_e32 v43, 0xffff0000, v87
	v_mul_f32_e32 v41, v41, v41
	v_fmac_f32_e32 v39, v38, v38
	v_add_f32_e32 v3, v37, v3
	v_lshlrev_b32_e32 v42, 16, v87
	v_mul_f32_e32 v43, v43, v43
	v_fmac_f32_e32 v41, v40, v40
	v_add_f32_e32 v3, v39, v3
	v_fmac_f32_e32 v43, v42, v42
	v_add_f32_e32 v3, v41, v3
	v_add_f32_e32 v3, v43, v3
	v_mov_b32_e32 v13, v3
	s_nop 1
	v_permlane32_swap_b32_e32 v3, v13
	v_add_f32_e32 v3, v3, v13
	ds_bpermute_b32 v13, v131, v3
	v_cmp_lt_i32_e64 s[0:1], v124, v122
	s_waitcnt lgkmcnt(0)
	v_max_f32_e32 v13, v13, v13
	v_cndmask_b32_e64 v14, v1, v124, s[0:1]
	v_lshlrev_b32_e32 v14, 2, v14
	v_max_f32_e32 v3, v3, v13
	ds_bpermute_b32 v13, v14, v3
	v_cmp_lt_i32_e64 s[0:1], v125, v122
	s_waitcnt lgkmcnt(0)
	v_max_f32_e32 v13, v13, v13
	v_cndmask_b32_e64 v14, v1, v125, s[0:1]
	v_lshlrev_b32_e32 v14, 2, v14
	v_max_f32_e32 v3, v3, v13
	ds_bpermute_b32 v13, v14, v3
	v_cmp_lt_i32_e64 s[0:1], v126, v122
	s_waitcnt lgkmcnt(0)
	v_max_f32_e32 v13, v13, v13
	v_cndmask_b32_e64 v14, v1, v126, s[0:1]
	v_lshlrev_b32_e32 v14, 2, v14
	v_max_f32_e32 v3, v3, v13
	ds_bpermute_b32 v13, v14, v3
	v_cmp_lt_i32_e64 s[0:1], v127, v122
	s_waitcnt lgkmcnt(0)
	v_max_f32_e32 v13, v13, v13
	v_cndmask_b32_e64 v14, v1, v127, s[0:1]
	v_max_f32_e32 v3, v3, v13
	v_lshlrev_b32_e32 v13, 2, v14
	ds_bpermute_b32 v13, v13, v3
	s_and_b32 s0, s4, 0x3fffffc0
	s_lshl_b32 s0, s0, 2
	s_add_i32 s29, s0, 0
	v_cmp_eq_u32_e64 s[0:1], 0, v135
	s_and_saveexec_b64 s[6:7], s[0:1]
	s_cbranch_execz .LBB0_339
	s_waitcnt lgkmcnt(0)
	v_max_f32_e32 v13, v13, v13
	v_max_f32_e32 v3, v3, v3
	v_max_f32_e32 v3, v3, v13
	v_mov_b32_e32 v13, s29
	ds_write_b32 v13, v3 offset:49152

.LBB0_1422:
	s_lshl_b32 s0, s87, 6
	s_and_b32 s89, s0, 0x2000
	s_bfe_u32 s3, s87, 0x30004
	s_mul_i32 s0, s89, 0xc00
	s_add_u32 s5, s16, s0
	s_addc_u32 s7, s20, 0
	s_lshl_b32 s97, s3, 7
	s_lshl_b32 s0, s3, 8
	s_add_u32 s0, s5, s0
	s_addc_u32 s1, s7, 0
	s_add_u32 s6, s5, s97
	s_addc_u32 s7, s7, 0
	s_lshl_b32 s5, s89, 12
	s_add_u32 s5, s18, s5
	s_addc_u32 s9, s83, 0
	s_lshl_b32 s3, s3, 9
	s_add_u32 s8, s5, s3
	s_addc_u32 s9, s9, 0
	s_lshl_b32 s3, s89, 7
	s_add_u32 s3, s33, s3
	s_addc_u32 s5, s24, 0
	s_lshl_b32 s10, s87, 8
	s_and_b32 s10, s10, 0xf00
	s_xor_b32 s11, s10, 0x1f00
	v_mov_b32_e32 v187, v182
	s_cmpk_lt_u32 s87, 0x100
	s_cselect_b32 s85, s11, s10
	v_readfirstlane_b32 s82, v187
	s_ashr_i32 s10, s82, 6
	v_and_b32_e32 v98, 63, v187
	v_lshlrev_b32_e32 v62, 4, v98
	s_mul_i32 s12, s10, 0xc00
	v_or_b32_e32 v19, s12, v62
	v_mul_hi_i32 v18, v19, s19
	v_lshrrev_b32_e32 v20, 31, v18
	v_ashrrev_i32_e32 v18, 6, v18
	v_add_u32_e32 v18, v18, v20
	v_mul_i32_i24_e32 v20, 0x180, v18
	v_sub_u32_e32 v19, v19, v20
	v_ashrrev_i32_e32 v20, 4, v19
	v_lshrrev_b32_e32 v21, 1, v18
	v_bitop3_b32 v20, v21, v20, 7 bitop3:0x6c
	v_cmp_lt_i32_e32 vcc, s17, v19
	v_lshlrev_b32_e32 v20, 3, v20
	v_ashrrev_i32_e32 v19, 31, v18
	v_cndmask_b32_e64 v21, 11, 6, vcc
	s_lshl_b32 s11, s10, 5
	v_lshlrev_b64 v[18:19], v21, v[18:19]
	v_add_u32_e32 v21, 0xffffff80, v20
	v_mov_b32_e32 v24, s9
	v_mov_b32_e32 v25, s5
	v_mov_b32_e32 v26, s8
	v_mov_b32_e32 v27, s3
	s_add_i32 s96, s11, s85
	s_mul_i32 s11, s10, 3
	v_cndmask_b32_e32 v20, v20, v21, vcc
	v_cndmask_b32_e32 v23, v24, v25, vcc
	v_cndmask_b32_e32 v22, v26, v27, vcc
	v_ashrrev_i32_e32 v21, 31, v20
	v_lshl_add_u64 v[18:19], v[18:19], 1, v[22:23]
	s_add_i32 s3, s11, 1
	v_lshl_add_u64 v[46:47], v[20:21], 1, v[18:19]
	v_lshl_or_b32 v19, s3, 10, v62
	v_mul_hi_i32 v18, v19, s19
	v_lshrrev_b32_e32 v20, 31, v18
	v_ashrrev_i32_e32 v18, 6, v18
	v_add_u32_e32 v18, v18, v20
	v_mul_i32_i24_e32 v20, 0x180, v18
	v_sub_u32_e32 v19, v19, v20
	v_ashrrev_i32_e32 v20, 4, v19
	v_lshrrev_b32_e32 v21, 1, v18
	v_cndmask_b32_e32 v76, v1, v183, vcc
	v_bitop3_b32 v20, v21, v20, 7 bitop3:0x6c
	v_cmp_lt_i32_e32 vcc, s17, v19
	v_lshlrev_b32_e32 v20, 3, v20
	v_ashrrev_i32_e32 v19, 31, v18
	v_cndmask_b32_e64 v21, 11, 6, vcc
	v_lshlrev_b64 v[18:19], v21, v[18:19]
	v_add_u32_e32 v21, 0xffffff80, v20
	v_cndmask_b32_e32 v20, v20, v21, vcc
	v_cndmask_b32_e32 v23, v24, v25, vcc
	v_cndmask_b32_e32 v22, v26, v27, vcc
	v_ashrrev_i32_e32 v21, 31, v20
	v_lshl_add_u64 v[18:19], v[18:19], 1, v[22:23]
	s_add_i32 s5, s11, 2
	v_lshl_add_u64 v[48:49], v[20:21], 1, v[18:19]
	v_lshl_or_b32 v19, s5, 10, v62
	v_mul_hi_i32 v18, v19, s19
	v_lshrrev_b32_e32 v20, 31, v18
	v_ashrrev_i32_e32 v18, 6, v18
	v_add_u32_e32 v18, v18, v20
	v_mul_i32_i24_e32 v20, 0x180, v18
	v_sub_u32_e32 v19, v19, v20
	v_ashrrev_i32_e32 v20, 4, v19
	v_lshrrev_b32_e32 v21, 1, v18
	v_cndmask_b32_e32 v77, v1, v183, vcc
	v_bitop3_b32 v20, v21, v20, 7 bitop3:0x6c
	v_cmp_lt_i32_e32 vcc, s17, v19
	v_lshlrev_b32_e32 v20, 3, v20
	v_ashrrev_i32_e32 v19, 31, v18
	v_cndmask_b32_e64 v21, 11, 6, vcc
	v_lshlrev_b64 v[18:19], v21, v[18:19]
	v_add_u32_e32 v21, 0xffffff80, v20
	v_cndmask_b32_e32 v20, v20, v21, vcc
	v_cndmask_b32_e32 v23, v24, v25, vcc
	v_cndmask_b32_e32 v22, v26, v27, vcc
	v_ashrrev_i32_e32 v21, 31, v20
	v_lshl_add_u64 v[18:19], v[18:19], 1, v[22:23]
	s_lshl_b32 s86, s10, 11
	v_lshl_add_u64 v[56:57], v[20:21], 1, v[18:19]
	s_ashr_i32 s12, s86, 8
	v_lshrrev_b32_e32 v19, 1, v187
	v_bfe_u32 v18, v187, 2, 2
	s_and_b32 s13, s12, -16
	v_and_b32_e32 v19, 8, v19
	s_lshr_b32 s12, s12, 1
	v_or3_b32 v18, v19, v18, s13
	v_lshlrev_b32_e32 v60, 3, v98
	v_and_or_b32 v18, s12, 4, v18
	v_and_b32_e32 v61, 24, v60
	v_and_b32_e32 v22, 32, v187
	v_ashrrev_i32_e32 v19, 31, v18
	v_lshlrev_b64 v[18:19], 12, v[18:19]
	v_or_b32_e32 v20, v61, v22
	v_lshl_add_u64 v[18:19], s[8:9], 0, v[18:19]
	v_lshlrev_b32_e32 v162, 1, v20
	v_lshl_add_u64 v[54:55], v[18:19], 0, v[162:163]
	s_mov_b64 s[8:9], 0x100
	s_lshl_b32 s74, s11, 10
	v_lshl_add_u64 v[50:51], v[54:55], 0, s[8:9]
	s_mov_b64 s[8:9], 0x180
	s_cmp_lg_u32 0, -1
	v_lshl_add_u64 v[18:19], v[54:55], 0, s[8:9]
	s_cselect_b32 s8, 0, 0
	s_add_i32 s9, s8, 0x8000
	s_lshl_b32 s75, s3, 10
	s_add_i32 s11, s74, s9
	s_mov_b32 s12, m0
	s_mov_b32 m0, s11
	s_nop 0
	global_load_lds_dwordx4 v[46:47], off
	s_mov_b32 m0, s12
	s_add_i32 s3, s75, s9
	s_lshl_b32 s5, s5, 10
	s_mov_b32 s11, m0
	s_mov_b32 m0, s3
	s_nop 0
	global_load_lds_dwordx4 v[48:49], off
	s_mov_b32 m0, s11
	s_add_i32 s3, s5, s9
	s_mov_b32 s9, m0
	s_mov_b32 m0, s3
	s_nop 0
	global_load_lds_dwordx4 v[56:57], off
	s_mov_b32 m0, s9
	s_add_i32 s3, s86, s8
	v_and_b32_e32 v189, 31, v187
	s_mov_b32 s9, m0
	s_mov_b32 m0, s3
	s_nop 0
	global_load_lds_dwordx4 v[50:51], off
	s_mov_b32 m0, s9
	s_or_b32 s3, s86, 0x400
	v_bfe_u32 v63, v187, 5, 1
	v_or_b32_e32 v52, s96, v189
	s_add_i32 s9, s3, s8
	s_mov_b32 s11, m0
	s_mov_b32 m0, s9
	s_nop 0
	global_load_lds_dwordx4 v[18:19], off
	s_mov_b32 m0, s11
	v_mov_b64_e32 v[18:19], s[6:7]
	v_ashrrev_i32_e32 v53, 31, v52
	v_lshlrev_b32_e32 v58, 4, v63
	v_mov_b32_e32 v59, v163
	v_mad_i64_i32 v[18:19], s[6:7], v52, s27, v[18:19]
	v_lshl_add_u64 v[34:35], v[18:19], 0, v[58:59]
	v_lshlrev_b64 v[68:69], 8, v[52:53]
	global_load_dwordx4 v[18:21], v[34:35], off offset:2048 nt
	v_or_b32_e32 v68, v68, v22
	v_lshl_add_u64 v[26:27], s[94:95], 0, v[68:69]
	v_mov_b64_e32 v[234:235], v[26:27]
	global_load_dwordx4 v[22:25], v[26:27], off
	s_nop 0
	global_load_dwordx4 v[26:29], v[26:27], off offset:16
	v_mov_b64_e32 v[30:31], s[0:1]
	v_mad_i64_i32 v[30:31], s[0:1], v52, s27, v[30:31]
	v_lshl_add_u64 v[30:31], v[30:31], 0, v[58:59]
	global_load_dwordx4 v[158:161], v[30:31], off nt
	global_load_dwordx4 v[154:157], v[30:31], off offset:32 nt
	global_load_dwordx4 v[150:153], v[30:31], off offset:64 nt
	global_load_dwordx4 v[146:149], v[30:31], off offset:96 nt
	global_load_dwordx4 v[142:145], v[30:31], off offset:128 nt
	global_load_dwordx4 v[138:141], v[30:31], off offset:160 nt
	global_load_dwordx4 v[134:137], v[30:31], off offset:192 nt
	global_load_dwordx4 v[130:133], v[30:31], off offset:224 nt
	s_nop 0
	global_load_dwordx4 v[30:33], v[34:35], off offset:2080 nt
	global_load_dwordx4 v[64:67], v[34:35], off offset:2112 nt
	global_load_dwordx4 v[38:41], v[34:35], off offset:2144 nt
	global_load_dwordx4 v[238:241], v[234:235], off offset:64
	global_load_dwordx4 v[242:245], v[234:235], off offset:80
	global_load_dwordx4 v[246:249], v[234:235], off offset:128
	global_load_dwordx4 v[250:253], v[234:235], off offset:144
	global_load_dwordx4 v[226:229], v[234:235], off offset:192
	global_load_dwordx4 v[230:233], v[234:235], off offset:208
	s_movk_i32 s9, 0x180
	v_cndmask_b32_e32 v78, v1, v183, vcc
	v_mov_b32_e32 v165, v163
	s_mov_b64 s[0:1], 0x40100
	s_mov_b64 s[6:7], 0x40180
	v_lshlrev_b32_e32 v186, 2, v63
	v_mad_u32_u24 v59, v189, s9, 0
	s_lshl_b32 s9, s10, 12
	v_lshlrev_b32_e32 v162, 1, v76
	v_lshlrev_b32_e32 v164, 1, v77
	v_sub_u32_e32 v192, v52, v186
	s_add_i32 s9, s9, 0
	v_lshlrev_b32_e32 v166, 1, v78
	v_lshl_add_u64 v[76:77], v[54:55], 0, s[0:1]
	v_lshl_add_u64 v[78:79], v[54:55], 0, s[6:7]
	v_lshl_add_u64 v[54:55], v[48:49], 0, v[164:165]
	s_add_i32 s9, s9, 0x14800
	v_add_u32_e32 v193, s9, v62
	s_add_i32 s10, s8, 0xe000
	s_add_i32 s11, s74, s10
	v_mov_b32_e32 v167, v163
	s_add_i32 s12, s75, s10
	s_addk_i32 s8, 0x4000
	s_add_i32 s10, s5, s10
	v_lshl_add_u64 v[56:57], v[56:57], 0, v[166:167]
	s_add_i32 s13, s86, s8
	s_waitcnt vmcnt(19)
	v_lshlrev_b32_e32 v34, 16, v18
	v_and_b32_e32 v35, 0xffff0000, v18
	s_waitcnt vmcnt(18)
	v_pk_mul_f32 v[36:37], v[22:23], v[34:35]
	v_pk_mul_f32 v[22:23], v[22:23], v[34:35] op_sel:[0,1] op_sel_hi:[1,0]
	v_sub_f32_e32 v18, v36, v37
	v_add_f32_e32 v22, v22, v23
	v_cvt_pk_bf16_f32 v34, v18, v22
	v_lshlrev_b32_e32 v18, 16, v19
	v_and_b32_e32 v19, 0xffff0000, v19
	v_pk_mul_f32 v[22:23], v[24:25], v[18:19]
	v_pk_mul_f32 v[18:19], v[24:25], v[18:19] op_sel:[0,1] op_sel_hi:[1,0]
	v_sub_f32_e32 v22, v22, v23
	v_add_f32_e32 v18, v18, v19
	v_cvt_pk_bf16_f32 v35, v22, v18
	v_lshlrev_b32_e32 v18, 16, v20
	v_and_b32_e32 v19, 0xffff0000, v20
	s_waitcnt vmcnt(17)
	v_pk_mul_f32 v[22:23], v[26:27], v[18:19]
	v_pk_mul_f32 v[18:19], v[26:27], v[18:19] op_sel:[0,1] op_sel_hi:[1,0]
	v_sub_f32_e32 v20, v22, v23
	v_add_f32_e32 v18, v18, v19
	v_cvt_pk_bf16_f32 v36, v20, v18
	v_lshlrev_b32_e32 v18, 16, v21
	v_and_b32_e32 v19, 0xffff0000, v21
	v_pk_mul_f32 v[20:21], v[28:29], v[18:19]
	v_pk_mul_f32 v[18:19], v[28:29], v[18:19] op_sel:[0,1] op_sel_hi:[1,0]
	v_sub_f32_e32 v20, v20, v21
	v_add_f32_e32 v18, v18, v19
	v_cvt_pk_bf16_f32 v37, v20, v18
	v_or_b32_e32 v18, 64, v68
	v_mov_b32_e32 v19, v69
	v_lshl_add_u64 v[22:23], s[94:95], 0, v[18:19]
	s_waitcnt vmcnt(8)
	v_lshlrev_b32_e32 v26, 16, v30
	v_and_b32_e32 v27, 0xffff0000, v30
	s_waitcnt vmcnt(7)
	v_lshlrev_b32_e32 v30, 16, v65
	s_waitcnt vmcnt(6)
	v_lshlrev_b32_e32 v48, 16, v40
	v_and_b32_e32 v49, 0xffff0000, v40
	v_lshlrev_b32_e32 v40, 16, v41
	v_and_b32_e32 v41, 0xffff0000, v41
	s_waitcnt vmcnt(5)
	v_pk_mul_f32 v[28:29], v[238:239], v[26:27]
	v_pk_mul_f32 v[18:19], v[238:239], v[26:27] op_sel:[0,1] op_sel_hi:[1,0]
	v_sub_f32_e32 v28, v28, v29
	v_add_f32_e32 v18, v18, v19
	v_cvt_pk_bf16_f32 v42, v28, v18
	v_lshlrev_b32_e32 v18, 16, v31
	v_and_b32_e32 v19, 0xffff0000, v31
	v_pk_mul_f32 v[26:27], v[240:241], v[18:19]
	v_pk_mul_f32 v[18:19], v[240:241], v[18:19] op_sel:[0,1] op_sel_hi:[1,0]
	v_sub_f32_e32 v26, v26, v27
	v_add_f32_e32 v18, v18, v19
	v_cvt_pk_bf16_f32 v43, v26, v18
	v_lshlrev_b32_e32 v18, 16, v32
	v_and_b32_e32 v19, 0xffff0000, v32
	s_waitcnt vmcnt(4)
	v_pk_mul_f32 v[20:21], v[242:243], v[18:19]
	v_pk_mul_f32 v[18:19], v[242:243], v[18:19] op_sel:[0,1] op_sel_hi:[1,0]
	v_sub_f32_e32 v20, v20, v21
	v_add_f32_e32 v18, v18, v19
	v_cvt_pk_bf16_f32 v44, v20, v18
	v_lshlrev_b32_e32 v18, 16, v33
	v_and_b32_e32 v19, 0xffff0000, v33
	v_pk_mul_f32 v[20:21], v[244:245], v[18:19]
	v_pk_mul_f32 v[18:19], v[244:245], v[18:19] op_sel:[0,1] op_sel_hi:[1,0]
	v_sub_f32_e32 v20, v20, v21
	v_add_f32_e32 v18, v18, v19
	v_cvt_pk_bf16_f32 v45, v20, v18
	v_or_b32_e32 v18, 0x80, v68
	v_mov_b32_e32 v19, v69
	v_lshl_add_u64 v[22:23], s[94:95], 0, v[18:19]
	v_or_b32_e32 v68, 0xc0, v68
	v_lshlrev_b32_e32 v28, 16, v64
	v_and_b32_e32 v29, 0xffff0000, v64
	v_and_b32_e32 v31, 0xffff0000, v65
	v_lshlrev_b32_e32 v32, 16, v66
	v_and_b32_e32 v33, 0xffff0000, v66
	v_lshlrev_b32_e32 v64, 16, v67
	v_and_b32_e32 v65, 0xffff0000, v67
	v_lshl_add_u64 v[26:27], s[94:95], 0, v[68:69]
	s_waitcnt vmcnt(3)
	v_pk_mul_f32 v[66:67], v[246:247], v[28:29]
	v_pk_mul_f32 v[18:19], v[246:247], v[28:29] op_sel:[0,1] op_sel_hi:[1,0]
	v_pk_mul_f32 v[28:29], v[248:249], v[30:31]
	v_pk_mul_f32 v[20:21], v[248:249], v[30:31] op_sel:[0,1] op_sel_hi:[1,0]
	s_waitcnt vmcnt(2)
	v_pk_mul_f32 v[30:31], v[250:251], v[32:33]
	v_pk_mul_f32 v[22:23], v[250:251], v[32:33] op_sel:[0,1] op_sel_hi:[1,0]
	v_pk_mul_f32 v[32:33], v[252:253], v[64:65]
	v_pk_mul_f32 v[24:25], v[252:253], v[64:65] op_sel:[0,1] op_sel_hi:[1,0]
	v_sub_f32_e32 v53, v66, v67
	v_add_f32_e32 v18, v18, v19
	v_sub_f32_e32 v19, v28, v29
	v_add_f32_e32 v20, v20, v21
	v_sub_f32_e32 v21, v30, v31
	v_add_f32_e32 v22, v22, v23
	v_sub_f32_e32 v23, v32, v33
	v_add_f32_e32 v24, v24, v25
	v_cvt_pk_bf16_f32 v64, v53, v18
	v_cvt_pk_bf16_f32 v65, v19, v20
	v_cvt_pk_bf16_f32 v66, v21, v22
	v_cvt_pk_bf16_f32 v67, v23, v24
	v_lshlrev_b32_e32 v53, 3, v187
	v_and_b32_e32 v63, 0x70, v53
	v_lshl_add_u64 v[52:53], v[46:47], 0, v[162:163]
	v_lshlrev_b32_e32 v46, 16, v38
	v_and_b32_e32 v47, 0xffff0000, v38
	v_lshlrev_b32_e32 v38, 16, v39
	v_and_b32_e32 v39, 0xffff0000, v39
	v_mov_b64_e32 v[32:33], v[16:17]
	v_mov_b64_e32 v[30:31], v[14:15]
	v_mov_b64_e32 v[28:29], v[12:13]
	v_mov_b64_e32 v[26:27], v[10:11]
	v_mov_b64_e32 v[24:25], v[8:9]
	v_mov_b64_e32 v[22:23], v[6:7]
	v_mov_b64_e32 v[20:21], v[4:5]
	v_mov_b64_e32 v[18:19], v[2:3]
	s_waitcnt vmcnt(1)
	v_pk_mul_f32 v[80:81], v[226:227], v[46:47]
	v_pk_mul_f32 v[46:47], v[226:227], v[46:47] op_sel:[0,1] op_sel_hi:[1,0]
	v_pk_mul_f32 v[68:69], v[228:229], v[38:39]
	v_pk_mul_f32 v[38:39], v[228:229], v[38:39] op_sel:[0,1] op_sel_hi:[1,0]
	s_waitcnt vmcnt(0)
	v_pk_mul_f32 v[70:71], v[230:231], v[48:49]
	v_pk_mul_f32 v[48:49], v[230:231], v[48:49] op_sel:[0,1] op_sel_hi:[1,0]
	v_pk_mul_f32 v[72:73], v[232:233], v[40:41]
	v_pk_mul_f32 v[40:41], v[232:233], v[40:41] op_sel:[0,1] op_sel_hi:[1,0]
	v_add_f32_e32 v39, v38, v39
	v_add_f32_e32 v41, v40, v41
	v_sub_f32_e32 v74, v80, v81
	v_add_f32_e32 v46, v46, v47
	v_sub_f32_e32 v47, v68, v69
	v_sub_f32_e32 v68, v70, v71
	v_add_f32_e32 v48, v48, v49
	v_sub_f32_e32 v49, v72, v73
	v_cvt_pk_bf16_f32 v38, v74, v46
	v_cvt_pk_bf16_f32 v39, v47, v39
	v_cvt_pk_bf16_f32 v40, v68, v48
	v_cvt_pk_bf16_f32 v41, v49, v41
	ds_write_b128 v193, v[34:37]
	ds_write_b128 v193, v[42:45] offset:1024
	ds_write_b128 v193, v[64:67] offset:2048
	ds_write_b128 v193, v[38:41] offset:3072
	s_waitcnt vmcnt(0)
	s_waitcnt lgkmcnt(0)
	s_barrier
	s_mov_b32 s0, m0
	s_mov_b32 m0, s11
	s_nop 0
	global_load_lds_dwordx4 v[52:53], off
	s_mov_b32 m0, s0
	s_nop 0
	s_mov_b32 s0, m0
	s_mov_b32 m0, s12
	s_nop 0
	global_load_lds_dwordx4 v[54:55], off
	s_mov_b32 m0, s0
	s_nop 0
	s_mov_b32 s0, m0
	s_mov_b32 m0, s10
	s_nop 0
	global_load_lds_dwordx4 v[56:57], off
	s_mov_b32 m0, s0
	s_nop 0
	s_mov_b32 s0, m0
	s_mov_b32 m0, s13
	s_nop 0
	global_load_lds_dwordx4 v[76:77], off
	s_mov_b32 m0, s0
	s_add_i32 s0, s3, s8
	s_mov_b32 s1, m0
	s_mov_b32 m0, s0
	s_nop 0
	global_load_lds_dwordx4 v[78:79], off
	s_mov_b32 m0, s1
	v_xad_u32 v194, v58, v63, v59
	ds_read_b128 v[64:67], v194 offset:32768
	ds_read_b128 v[68:71], v194 offset:45056
	s_waitcnt lgkmcnt(1)
	v_mfma_f32_32x32x16_bf16 v[34:49], v[64:67], v[158:161], v[18:33]
	v_or_b32_e32 v64, 32, v58
	v_xad_u32 v195, v64, v63, v59
	s_waitcnt lgkmcnt(0)
	v_mfma_f32_32x32x16_bf16 v[18:33], v[68:71], v[158:161], v[18:33]
	ds_read_b128 v[64:67], v195 offset:32768
	ds_read_b128 v[68:71], v195 offset:45056
	s_waitcnt lgkmcnt(1)
	v_mfma_f32_32x32x16_bf16 v[34:49], v[64:67], v[154:157], v[34:49]
	s_waitcnt lgkmcnt(0)
	v_mfma_f32_32x32x16_bf16 v[18:33], v[68:71], v[154:157], v[18:33]
	v_or_b32_e32 v64, 64, v58
	v_xad_u32 v196, v64, v63, v59
	ds_read_b128 v[64:67], v196 offset:32768
	ds_read_b128 v[68:71], v196 offset:45056
	v_or_b32_e32 v58, 0x60, v58
	v_xad_u32 v197, v58, v63, v59
	s_waitcnt lgkmcnt(1)
	v_mfma_f32_32x32x16_bf16 v[34:49], v[64:67], v[150:153], v[34:49]
	s_waitcnt lgkmcnt(0)
	v_mfma_f32_32x32x16_bf16 v[18:33], v[68:71], v[150:153], v[18:33]
	ds_read_b128 v[64:67], v197 offset:32768
	ds_read_b128 v[68:71], v197 offset:45056
	s_waitcnt lgkmcnt(1)
	v_mfma_f32_32x32x16_bf16 v[34:49], v[64:67], v[146:149], v[34:49]
	s_waitcnt lgkmcnt(0)
	v_mfma_f32_32x32x16_bf16 v[18:33], v[68:71], v[146:149], v[18:33]
	ds_read_b128 v[64:67], v194 offset:32896
	ds_read_b128 v[68:71], v194 offset:45184
	s_waitcnt lgkmcnt(1)
	v_mfma_f32_32x32x16_bf16 v[34:49], v[64:67], v[142:145], v[34:49]
	s_waitcnt lgkmcnt(0)
	v_mfma_f32_32x32x16_bf16 v[18:33], v[68:71], v[142:145], v[18:33]
	ds_read_b128 v[64:67], v195 offset:32896
	ds_read_b128 v[68:71], v195 offset:45184
	s_waitcnt lgkmcnt(1)
	v_mfma_f32_32x32x16_bf16 v[34:49], v[64:67], v[138:141], v[34:49]
	s_waitcnt lgkmcnt(0)
	v_mfma_f32_32x32x16_bf16 v[18:33], v[68:71], v[138:141], v[18:33]
	ds_read_b128 v[64:67], v196 offset:32896
	ds_read_b128 v[68:71], v196 offset:45184
	s_waitcnt lgkmcnt(1)
	v_mfma_f32_32x32x16_bf16 v[34:49], v[64:67], v[134:137], v[34:49]
	s_waitcnt lgkmcnt(0)
	v_mfma_f32_32x32x16_bf16 v[18:33], v[68:71], v[134:137], v[18:33]
	ds_read_b128 v[64:67], v197 offset:32896
	ds_read_b128 v[68:71], v197 offset:45184
	s_waitcnt lgkmcnt(1)
	v_mfma_f32_32x32x16_bf16 v[34:49], v[64:67], v[130:133], v[34:49]
	s_waitcnt lgkmcnt(0)
	v_mfma_f32_32x32x16_bf16 v[18:33], v[68:71], v[130:133], v[18:33]
	ds_read_b128 v[64:67], v194 offset:33024
	ds_read_b128 v[68:71], v193
	ds_read_b128 v[72:75], v193 offset:1024
	ds_read_b128 v[76:79], v194 offset:45312
	s_waitcnt lgkmcnt(2)
	v_mfma_f32_32x32x16_bf16 v[34:49], v[64:67], v[68:71], v[34:49]
	s_waitcnt lgkmcnt(0)
	v_mfma_f32_32x32x16_bf16 v[18:33], v[76:79], v[68:71], v[18:33]
	ds_read_b128 v[64:67], v195 offset:33024
	ds_read_b128 v[68:71], v195 offset:45312
	s_waitcnt lgkmcnt(1)
	v_mfma_f32_32x32x16_bf16 v[34:49], v[64:67], v[72:75], v[34:49]
	s_waitcnt lgkmcnt(0)
	v_mfma_f32_32x32x16_bf16 v[18:33], v[68:71], v[72:75], v[18:33]
	ds_read_b128 v[64:67], v196 offset:33024
	ds_read_b128 v[68:71], v193 offset:2048
	ds_read_b128 v[72:75], v193 offset:3072
	ds_read_b128 v[76:79], v196 offset:45312
	s_waitcnt lgkmcnt(2)
	v_mfma_f32_32x32x16_bf16 v[34:49], v[64:67], v[68:71], v[34:49]
	s_waitcnt lgkmcnt(0)
	v_mfma_f32_32x32x16_bf16 v[18:33], v[76:79], v[68:71], v[18:33]
	ds_read_b128 v[64:67], v197 offset:33024
	ds_read_b128 v[68:71], v197 offset:45312
	s_waitcnt lgkmcnt(1)
	v_mfma_f32_32x32x16_bf16 v[34:49], v[64:67], v[72:75], v[34:49]
	s_waitcnt lgkmcnt(0)
	v_mfma_f32_32x32x16_bf16 v[18:33], v[68:71], v[72:75], v[18:33]
	s_cmp_gt_i32 s96, 62
	s_cbranch_scc1 .LBB0_1424
	v_cmp_gt_i32_e64 s[64:65], 26, v192
	v_cmp_gt_i32_e64 s[66:67], 27, v192
	v_cmp_gt_i32_e64 s[62:63], 25, v192
	s_and_b64 s[64:65], s[66:67], s[64:65]
	v_cmp_gt_i32_e64 s[60:61], 24, v192
	s_and_b64 s[62:63], s[64:65], s[62:63]
	v_cmp_gt_i32_e64 s[58:59], 19, v192
	s_and_b64 s[60:61], s[62:63], s[60:61]
	v_cmp_gt_i32_e64 s[56:57], 18, v192
	s_and_b64 s[58:59], s[60:61], s[58:59]
	v_cmp_gt_i32_e64 s[54:55], 17, v192
	s_and_b64 s[56:57], s[58:59], s[56:57]
	v_cmp_gt_i32_e64 s[52:53], 16, v192
	s_and_b64 s[54:55], s[56:57], s[54:55]
	v_cmp_gt_i32_e64 s[50:51], 11, v192
	s_and_b64 s[52:53], s[54:55], s[52:53]
	v_cmp_gt_i32_e64 s[48:49], 10, v192
	s_and_b64 s[50:51], s[52:53], s[50:51]
	v_cmp_gt_i32_e64 s[46:47], 9, v192
	s_and_b64 s[48:49], s[50:51], s[48:49]
	v_cmp_gt_i32_e64 s[44:45], 8, v192
	s_and_b64 s[46:47], s[48:49], s[46:47]
	v_cmp_gt_i32_e64 s[42:43], 3, v192
	s_and_b64 s[44:45], s[46:47], s[44:45]
	v_cmp_gt_i32_e64 s[40:41], 2, v192
	s_and_b64 s[42:43], s[44:45], s[42:43]
	v_cmp_gt_i32_e64 s[38:39], 1, v192
	s_and_b64 s[40:41], s[42:43], s[40:41]
	v_cmp_gt_i32_e64 s[36:37], 0, v192
	s_and_b64 s[38:39], s[40:41], s[38:39]
	s_and_b64 s[36:37], s[38:39], s[36:37]
	v_cmp_gt_i32_e64 s[34:35], 58, v192
	v_cndmask_b32_e64 v34, v34, v185, s[36:37]
	v_cmp_gt_i32_e64 s[36:37], 59, v192
	v_cmp_gt_i32_e64 s[30:31], 57, v192
	s_and_b64 s[34:35], s[36:37], s[34:35]
	v_cmp_gt_i32_e64 s[28:29], 56, v192
	s_and_b64 s[30:31], s[34:35], s[30:31]
	v_cmp_gt_i32_e64 s[0:1], 32, v192
	s_mov_b64 s[92:93], s[22:23]
	s_mov_b64 s[22:23], s[72:73]
	s_mov_b32 s72, s84
	s_mov_b32 s84, s4
	s_mov_b32 s4, s26
	v_cmp_gt_i32_e64 s[26:27], 51, v192
	s_and_b64 s[28:29], s[30:31], s[28:29]
	v_writelane_b32 v236, s0, 17
	s_mov_b32 s21, s24
	v_cmp_gt_i32_e64 s[24:25], 50, v192
	s_and_b64 s[26:27], s[28:29], s[26:27]
	v_writelane_b32 v236, s1, 18
	v_cmp_gt_i32_e64 s[0:1], 49, v192
	s_and_b64 s[24:25], s[26:27], s[24:25]
	v_cmp_gt_i32_e32 vcc, 48, v192
	s_and_b64 s[0:1], s[24:25], s[0:1]
	v_cmp_gt_i32_e64 s[90:91], 43, v192
	v_cndmask_b32_e64 v27, v27, v185, s[0:1]
	s_and_b64 s[0:1], s[0:1], vcc
	v_cmp_gt_i32_e64 s[80:81], 42, v192
	v_cndmask_b32_e64 v26, v26, v185, s[0:1]
	s_and_b64 s[0:1], s[0:1], s[90:91]
	v_cmp_gt_i32_e64 s[14:15], 41, v192
	v_cndmask_b32_e64 v25, v25, v185, s[0:1]
	s_and_b64 s[0:1], s[0:1], s[80:81]
	v_cmp_gt_i32_e64 s[12:13], 40, v192
	v_cndmask_b32_e64 v24, v24, v185, s[0:1]
	s_and_b64 s[0:1], s[0:1], s[14:15]
	v_cmp_gt_i32_e64 s[10:11], 35, v192
	v_cndmask_b32_e64 v23, v23, v185, s[0:1]
	s_and_b64 s[0:1], s[0:1], s[12:13]
	v_cmp_gt_i32_e64 s[8:9], 34, v192
	v_cndmask_b32_e64 v22, v22, v185, s[0:1]
	s_and_b64 s[0:1], s[0:1], s[10:11]
	v_cmp_gt_i32_e64 s[6:7], 33, v192
	v_cndmask_b32_e64 v21, v21, v185, s[0:1]
	s_and_b64 s[0:1], s[0:1], s[8:9]
	v_cndmask_b32_e64 v20, v20, v185, s[0:1]
	s_and_b64 s[0:1], s[0:1], s[6:7]
	v_readlane_b32 s6, v236, 17
	v_readlane_b32 s7, v236, 18
	s_and_b64 vcc, s[0:1], s[6:7]
	v_cndmask_b32_e64 v49, v49, v185, s[66:67]
	v_cndmask_b32_e64 v48, v48, v185, s[64:65]
	v_cndmask_b32_e64 v47, v47, v185, s[62:63]
	v_cndmask_b32_e64 v46, v46, v185, s[60:61]
	v_cndmask_b32_e64 v45, v45, v185, s[58:59]
	v_cndmask_b32_e64 v44, v44, v185, s[56:57]
	v_cndmask_b32_e64 v43, v43, v185, s[54:55]
	v_cndmask_b32_e64 v42, v42, v185, s[52:53]
	v_cndmask_b32_e64 v41, v41, v185, s[50:51]
	v_cndmask_b32_e64 v40, v40, v185, s[48:49]
	v_cndmask_b32_e64 v39, v39, v185, s[46:47]
	v_cndmask_b32_e64 v38, v38, v185, s[44:45]
	v_cndmask_b32_e64 v37, v37, v185, s[42:43]
	v_cndmask_b32_e64 v36, v36, v185, s[40:41]
	v_cndmask_b32_e64 v35, v35, v185, s[38:39]
	v_cndmask_b32_e64 v33, v33, v185, s[36:37]
	v_cndmask_b32_e64 v32, v32, v185, s[34:35]
	v_cndmask_b32_e64 v31, v31, v185, s[30:31]
	s_mov_b64 s[30:31], 0x80000
	v_cndmask_b32_e64 v30, v30, v185, s[28:29]
	v_cndmask_b32_e64 v29, v29, v185, s[26:27]
	s_movk_i32 s27, 0xc00
	s_mov_b32 s26, s4
	s_mov_b32 s4, s84
	v_cndmask_b32_e64 v28, v28, v185, s[24:25]
	s_mov_b32 s24, s21
	s_mov_b32 s84, s72
	s_mov_b64 s[72:73], s[22:23]
	s_mov_b64 s[22:23], s[92:93]
	v_cndmask_b32_e64 v19, v19, v185, s[0:1]
	v_cndmask_b32_e32 v18, v18, v185, vcc
